# pool mixer: next item's gate loads issued one at a time in the first group's MFMA/output section instead of the item-top burst
# speedup vs baseline: 1.0006x; 1.0006x over previous
.LBB0_919:
	s_or_b64 exec, exec, s[6:7]
	ds_read_b128 v[160:163], v154
	ds_read_b128 v[164:167], v155
	ds_read_b128 v[168:171], v159
	v_mov_b32_e32 v197, v196
	v_mov_b32_e32 v193, v177
	s_add_i32 s8, s8, s5
	s_waitcnt lgkmcnt(0)
	v_lshlrev_b32_e32 v154, 16, v160
	v_and_b32_e32 v155, 0xffff0000, v160
	v_add_f32_e32 v154, v222, v154
	v_add_f32_e32 v155, v223, v155
	v_lshlrev_b32_e32 v158, 16, v164
	v_and_b32_e32 v159, 0xffff0000, v164
	v_add_f32_e32 v154, v154, v158
	v_add_f32_e32 v155, v155, v159
	v_lshlrev_b32_e32 v158, 16, v168
	v_and_b32_e32 v159, 0xffff0000, v168
	v_add_f32_e32 v154, v154, v158
	v_add_f32_e32 v155, v155, v159
	v_lshlrev_b32_e32 v158, 16, v161
	v_and_b32_e32 v159, 0xffff0000, v161
	v_add_f32_e32 v148, v148, v158
	v_add_f32_e32 v149, v149, v159
	v_lshlrev_b32_e32 v158, 16, v165
	v_and_b32_e32 v159, 0xffff0000, v165
	v_add_f32_e32 v148, v148, v158
	v_add_f32_e32 v149, v149, v159
	v_lshlrev_b32_e32 v158, 16, v169
	v_and_b32_e32 v159, 0xffff0000, v169
	v_add_f32_e32 v148, v148, v158
	v_add_f32_e32 v149, v149, v159
	v_fma_f32 v154, v196, v154, -v206
	v_fma_f32 v155, v197, v155, -v207
	v_fma_f32 v144, v196, v148, -v144
	v_fma_f32 v145, v197, v149, -v145
	v_cvt_pk_bf16_f32 v154, v154, v155
	v_cvt_pk_bf16_f32 v155, v144, v145
	v_lshlrev_b32_e32 v144, 16, v162
	v_and_b32_e32 v145, 0xffff0000, v162
	v_add_f32_e32 v144, v156, v144
	v_add_f32_e32 v145, v157, v145
	v_lshlrev_b32_e32 v148, 16, v166
	v_and_b32_e32 v149, 0xffff0000, v166
	v_add_f32_e32 v144, v144, v148
	v_add_f32_e32 v145, v145, v149
	v_lshlrev_b32_e32 v148, 16, v170
	v_and_b32_e32 v149, 0xffff0000, v170
	v_add_f32_e32 v144, v144, v148
	v_add_f32_e32 v145, v145, v149
	v_lshlrev_b32_e32 v148, 16, v167
	v_fma_f32 v144, v196, v144, -v152
	v_fma_f32 v145, v197, v145, -v153
	v_and_b32_e32 v149, 0xffff0000, v167
	v_cvt_pk_bf16_f32 v156, v144, v145
	v_lshlrev_b32_e32 v144, 16, v163
	v_and_b32_e32 v145, 0xffff0000, v163
	v_add_f32_e32 v144, v150, v144
	v_add_f32_e32 v145, v151, v145
	v_lshlrev_b32_e32 v152, 16, v171
	v_add_f32_e32 v144, v144, v148
	v_add_f32_e32 v145, v145, v149
	v_and_b32_e32 v153, 0xffff0000, v171
	v_mfma_f32_16x16x32_bf16 v[148:151], v[48:51], v[140:143], 0
	v_add_f32_e64 v144, v144, v152
	v_add_f32_e64 v145, v145, v153
	v_lshl_add_u64 v[152:153], v[194:195], 0, v[192:193]
	v_fma_f32 v144, v196, v144, -v146
	v_fma_f32 v145, v197, v145, -v147
	v_mfma_f32_16x16x32_bf16 v[158:161], v[72:75], v[140:143], 0
	v_cvt_pk_bf16_f32 v157, v144, v145
	s_and_b64 vcc, exec, s[0:1]
	s_mov_b32 s6, s9
	v_mfma_f32_16x16x32_bf16 v[144:147], v[52:55], v[154:157], v[148:151]
	v_mfma_f32_16x16x32_bf16 v[148:151], v[64:67], v[140:143], 0
	v_mfma_f32_16x16x32_bf16 v[140:143], v[88:91], v[140:143], 0
	s_nop 5
	v_mul_f32_e64 v144, v60, v144
	v_mul_f32_e64 v145, v61, v145
	v_mul_f32_e32 v146, v62, v146
	v_mul_f32_e32 v147, v63, v147
	v_mfma_f32_16x16x32_bf16 v[148:151], v[68:71], v[154:157], v[148:151]
	v_mfma_f32_16x16x32_bf16 v[158:161], v[76:79], v[154:157], v[158:161]
	v_mfma_f32_16x16x32_bf16 v[140:143], v[92:95], v[154:157], v[140:143]
	v_lshlrev_b32_e32 v154, 16, v120
	v_and_b32_e32 v155, 0xffff0000, v120
	v_mul_f32_e32 v144, v144, v154
	v_mul_f32_e32 v145, v145, v155
	s_nop 0
	v_cvt_pk_bf16_f32 v120, v144, v145
	v_lshlrev_b32_e32 v144, 16, v121
	v_and_b32_e32 v145, 0xffff0000, v121
	v_mul_f32_e32 v144, v146, v144
	v_mul_f32_e32 v145, v147, v145
	v_mul_f32_e32 v146, v56, v148
	v_mul_f32_e32 v147, v57, v149
	v_lshlrev_b32_e32 v148, 16, v122
	v_and_b32_e32 v149, 0xffff0000, v122
	v_mul_f32_e32 v146, v146, v148
	v_mul_f32_e32 v147, v147, v149
	v_cvt_pk_bf16_f32 v121, v144, v145
	v_mul_f32_e32 v144, v58, v150
	v_mul_f32_e32 v145, v59, v151
	v_cvt_pk_bf16_f32 v122, v146, v147
	v_lshlrev_b32_e32 v146, 16, v123
	v_and_b32_e32 v147, 0xffff0000, v123
	v_mul_f32_e32 v144, v144, v146
	v_mul_f32_e32 v145, v145, v147
	s_nop 0
	v_cvt_pk_bf16_f32 v123, v144, v145
	global_store_dwordx4 v[152:153], v[120:123], off
	v_lshlrev_b32_e32 v144, 16, v112
	v_and_b32_e32 v145, 0xffff0000, v112
	v_mul_f32_e32 v122, v84, v158
	v_mul_f32_e32 v123, v85, v159
	v_mul_f32_e32 v120, v86, v160
	v_mul_f32_e32 v121, v87, v161
	v_mul_f32_e32 v122, v122, v144
	v_mul_f32_e32 v123, v123, v145
	s_waitcnt vmcnt(6)
	v_mov_b64_e32 v[146:147], v[126:127]
	v_cvt_pk_bf16_f32 v112, v122, v123
	v_lshlrev_b32_e32 v122, 16, v113
	v_and_b32_e32 v123, 0xffff0000, v113
	v_mul_f32_e32 v120, v120, v122
	v_mul_f32_e32 v121, v121, v123
	v_mul_f32_e32 v122, v80, v140
	v_mul_f32_e32 v123, v81, v141
	v_lshlrev_b32_e32 v140, 16, v114
	v_and_b32_e32 v141, 0xffff0000, v114
	v_mul_f32_e32 v122, v122, v140
	v_mul_f32_e32 v123, v123, v141
	v_cvt_pk_bf16_f32 v113, v120, v121
	v_mul_f32_e32 v120, v82, v142
	v_mul_f32_e32 v121, v83, v143
	v_cvt_pk_bf16_f32 v114, v122, v123
	v_lshlrev_b32_e32 v122, 16, v115
	v_and_b32_e32 v123, 0xffff0000, v115
	v_mul_f32_e32 v120, v120, v122
	v_mul_f32_e32 v121, v121, v123
	s_waitcnt vmcnt(5)
	v_mov_b64_e32 v[142:143], v[130:131]
	v_cvt_pk_bf16_f32 v115, v120, v121
	global_store_dwordx4 v[152:153], v[112:115], off offset:64
	s_waitcnt vmcnt(4)
	v_mov_b64_e32 v[120:121], v[132:133]
	v_mov_b64_e32 v[144:145], v[124:125]
	s_waitcnt vmcnt(2)
	v_mov_b64_e32 v[112:113], v[136:137]
	v_mov_b64_e32 v[140:141], v[128:129]
	v_mov_b64_e32 v[122:123], v[134:135]
	v_mov_b64_e32 v[114:115], v[138:139]
	s_cbranch_vccnz .LBB0_938

.LBB0_934:
	s_or_b64 exec, exec, s[6:7]
	s_ashr_i32 s3, s8, 31
	v_mov_b32_e32 v161, s3
	v_or_b32_e32 v160, s8, v188
	v_lshlrev_b64 v[160:161], 11, v[160:161]
	v_lshl_add_u64 v[194:195], v[186:187], 0, v[160:161]
	global_load_dwordx4 v[124:127], v[128:129], off offset:512
	v_mfma_f32_16x16x32_bf16 v[160:163], v[0:3], v[148:151], 0
	v_cvt_pk_bf16_f32 v155, v156, v157
	v_mfma_f32_16x16x32_bf16 v[164:167], v[16:19], v[148:151], 0
	s_nop 0
	v_mfma_f32_16x16x32_bf16 v[160:163], v[4:7], v[152:155], v[160:163]
	v_mfma_f32_16x16x32_bf16 v[168:171], v[24:27], v[148:151], 0
	v_mfma_f32_16x16x32_bf16 v[148:151], v[40:43], v[148:151], 0
	s_nop 5
	v_mul_f32_e64 v156, v12, v160
	v_mul_f32_e64 v157, v13, v161
	v_lshlrev_b32_e32 v160, 16, v144
	v_and_b32_e32 v161, 0xffff0000, v144
	v_mfma_f32_16x16x32_bf16 v[164:167], v[20:23], v[152:155], v[164:167]
	v_mul_f32_e64 v156, v156, v160
	v_mul_f32_e64 v157, v157, v161
	v_lshlrev_b32_e32 v160, 16, v146
	v_cvt_pk_bf16_f32 v144, v156, v157
	v_mfma_f32_16x16x32_bf16 v[168:171], v[28:31], v[152:155], v[168:171]
	v_lshlrev_b32_e32 v156, 16, v145
	v_and_b32_e32 v157, 0xffff0000, v145
	v_and_b32_e32 v161, 0xffff0000, v146
	v_mfma_f32_16x16x32_bf16 v[148:151], v[44:47], v[152:155], v[148:151]
	global_load_dwordx4 v[128:131], v[128:129], off offset:576
	v_mul_f32_e64 v154, v14, v162
	v_mul_f32_e64 v155, v15, v163
	v_lshl_add_u64 v[152:153], v[194:195], 0, v[176:177]
	v_mul_f32_e32 v154, v154, v156
	v_mul_f32_e32 v155, v155, v157
	v_mul_f32_e32 v156, v8, v164
	v_mul_f32_e32 v157, v9, v165
	v_cvt_pk_bf16_f32 v145, v154, v155
	v_mul_f32_e32 v156, v156, v160
	v_mul_f32_e32 v157, v157, v161
	v_mul_f32_e32 v154, v10, v166
	v_mul_f32_e32 v155, v11, v167
	v_cvt_pk_bf16_f32 v146, v156, v157
	v_lshlrev_b32_e32 v156, 16, v147
	v_and_b32_e32 v157, 0xffff0000, v147
	v_mul_f32_e32 v154, v154, v156
	v_mul_f32_e32 v155, v155, v157
	s_nop 0
	v_cvt_pk_bf16_f32 v147, v154, v155
	global_store_dwordx4 v[152:153], v[144:147], off
	global_load_dwordx4 v[132:135], v[136:137], off offset:512
	v_lshlrev_b32_e32 v154, 16, v140
	v_and_b32_e32 v155, 0xffff0000, v140
	v_mul_f32_e32 v146, v36, v168
	v_mul_f32_e32 v147, v37, v169
	v_mul_f32_e32 v144, v38, v170
	v_mul_f32_e32 v145, v39, v171
	v_mul_f32_e32 v146, v146, v154
	v_mul_f32_e32 v147, v147, v155
	s_nop 0
	v_cvt_pk_bf16_f32 v140, v146, v147
	v_lshlrev_b32_e32 v146, 16, v141
	v_and_b32_e32 v147, 0xffff0000, v141
	v_mul_f32_e32 v144, v144, v146
	v_mul_f32_e32 v145, v145, v147
	v_mul_f32_e32 v146, v32, v148
	v_mul_f32_e32 v147, v33, v149
	v_lshlrev_b32_e32 v148, 16, v142
	v_and_b32_e32 v149, 0xffff0000, v142
	v_mul_f32_e32 v146, v146, v148
	v_mul_f32_e32 v147, v147, v149
	v_cvt_pk_bf16_f32 v141, v144, v145
	v_mul_f32_e32 v144, v34, v150
	v_mul_f32_e32 v145, v35, v151
	v_cvt_pk_bf16_f32 v142, v146, v147
	v_lshlrev_b32_e32 v146, 16, v143
	v_and_b32_e32 v147, 0xffff0000, v143
	v_mul_f32_e32 v144, v144, v146
	v_mul_f32_e32 v145, v145, v147
	s_nop 0
	v_cvt_pk_bf16_f32 v143, v144, v145
	global_store_dwordx4 v[152:153], v[140:143], off offset:64
	global_load_dwordx4 v[136:139], v[136:137], off offset:576
	s_and_saveexec_b64 s[6:7], s[36:37]
	s_xor_b64 s[6:7], exec, s[6:7]
	s_cbranch_execz .LBB0_936
	v_add_u32_e32 v140, 4, v158
	v_min_u32_e32 v140, s2, v140
	v_sub_u32_e64 v141, v158, 4 clamp
	v_sub_u32_e32 v140, v140, v141
	v_cvt_f32_i32_e32 v140, v140
	v_div_scale_f32 v141, s[10:11], v140, v140, 1.0
	v_rcp_f32_e32 v142, v141
	s_nop 0
	v_fma_f32 v143, -v141, v142, 1.0
	v_fmac_f32_e32 v142, v143, v142
	v_div_scale_f32 v143, vcc, 1.0, v140, 1.0
	v_mul_f32_e32 v144, v143, v142
	v_fma_f32 v145, -v141, v144, v143
	v_fmac_f32_e32 v144, v145, v142
	v_fma_f32 v141, -v141, v144, v143
	v_div_fmas_f32 v141, v141, v142, v144
	v_div_fixup_f32 v196, v141, v140, 1.0
	ds_read_b128 v[140:143], v244 offset:2112
	s_waitcnt lgkmcnt(0)
	v_lshlrev_b32_e32 v164, 16, v140
	v_and_b32_e32 v165, 0xffff0000, v140
	v_lshlrev_b32_e32 v166, 16, v141
	v_and_b32_e32 v167, 0xffff0000, v141
	v_lshlrev_b32_e32 v168, 16, v142
	v_and_b32_e32 v169, 0xffff0000, v142
	v_lshlrev_b32_e32 v170, 16, v143
	v_and_b32_e32 v171, 0xffff0000, v143
	ds_read_b128 v[140:143], v244 offset:2640
	v_add_f32_e32 v164, 0, v164
	v_add_f32_e32 v165, 0, v165
	s_waitcnt lgkmcnt(0)
	v_lshlrev_b32_e32 v172, 16, v140
	v_and_b32_e32 v173, 0xffff0000, v140
	v_lshlrev_b32_e32 v174, 16, v141
	v_and_b32_e32 v175, 0xffff0000, v141
	v_lshlrev_b32_e32 v198, 16, v142
	v_and_b32_e32 v199, 0xffff0000, v142
	v_lshlrev_b32_e32 v200, 16, v143
	v_and_b32_e32 v201, 0xffff0000, v143
	ds_read_b128 v[140:143], v244 offset:3168
	ds_read_b128 v[144:147], v244 offset:3696
	ds_read_b128 v[148:151], v244 offset:4224
	ds_read_b128 v[152:155], v244 offset:4752
	ds_read_b128 v[156:159], v244 offset:5280
	ds_read_b128 v[160:163], v244 offset:5808
	v_add_f32_e32 v164, v164, v172
	v_add_f32_e32 v165, v165, v173
	s_waitcnt lgkmcnt(5)
	v_lshlrev_b32_e32 v172, 16, v140
	v_and_b32_e32 v173, 0xffff0000, v140
	v_add_f32_e32 v164, v164, v172
	v_add_f32_e32 v165, v165, v173
	s_waitcnt lgkmcnt(4)
	v_lshlrev_b32_e32 v172, 16, v144
	v_and_b32_e32 v173, 0xffff0000, v144
	v_add_f32_e32 v164, v164, v172
	v_add_f32_e32 v165, v165, v173
	s_waitcnt lgkmcnt(3)
	v_lshlrev_b32_e32 v172, 16, v148
	v_and_b32_e32 v173, 0xffff0000, v148
	v_add_f32_e32 v164, v164, v172
	v_add_f32_e32 v165, v165, v173
	s_waitcnt lgkmcnt(2)
	v_lshlrev_b32_e32 v202, 16, v152
	v_and_b32_e32 v203, 0xffff0000, v152
	v_add_f32_e32 v164, v164, v202
	v_add_f32_e32 v165, v165, v203
	s_waitcnt lgkmcnt(1)
	v_lshlrev_b32_e32 v202, 16, v156
	v_and_b32_e32 v203, 0xffff0000, v156
	v_add_f32_e32 v164, v164, v202
	v_add_f32_e32 v165, v165, v203
	s_waitcnt lgkmcnt(0)
	v_lshlrev_b32_e32 v202, 16, v160
	v_and_b32_e32 v203, 0xffff0000, v160
	v_add_f32_e32 v164, v164, v202
	v_add_f32_e32 v165, v165, v203
	v_lshlrev_b32_e32 v144, 16, v145
	v_fma_f32 v164, v196, v164, -v172
	v_fma_f32 v165, v196, v165, -v173
	v_cvt_pk_bf16_f32 v140, v164, v165
	v_add_f32_e32 v164, 0, v166
	v_add_f32_e32 v165, 0, v167
	v_lshlrev_b32_e32 v166, 16, v141
	v_add_f32_e32 v164, v164, v174
	v_add_f32_e32 v165, v165, v175
	v_and_b32_e32 v167, 0xffff0000, v141
	v_add_f32_e32 v164, v164, v166
	v_add_f32_e32 v165, v165, v167
	v_and_b32_e32 v145, 0xffff0000, v145
	v_add_f32_e32 v144, v164, v144
	v_add_f32_e32 v145, v165, v145
	v_lshlrev_b32_e32 v148, 16, v149
	v_and_b32_e32 v149, 0xffff0000, v149
	v_add_f32_e32 v144, v144, v148
	v_add_f32_e32 v145, v145, v149
	v_lshlrev_b32_e32 v152, 16, v153
	v_and_b32_e32 v153, 0xffff0000, v153
	v_add_f32_e32 v144, v144, v152
	v_add_f32_e32 v145, v145, v153
	v_lshlrev_b32_e32 v152, 16, v157
	v_and_b32_e32 v153, 0xffff0000, v157
	v_add_f32_e32 v144, v144, v152
	v_add_f32_e32 v145, v145, v153
	v_lshlrev_b32_e32 v152, 16, v161
	v_and_b32_e32 v153, 0xffff0000, v161
	v_add_f32_e32 v144, v144, v152
	v_add_f32_e32 v145, v145, v153
	v_lshlrev_b32_e32 v152, 16, v154
	v_fma_f32 v144, v196, v144, -v148
	v_fma_f32 v145, v196, v145, -v149
	v_cvt_pk_bf16_f32 v141, v144, v145
	v_add_f32_e32 v144, 0, v168
	v_add_f32_e32 v145, 0, v169
	v_lshlrev_b32_e32 v148, 16, v142
	v_add_f32_e32 v144, v144, v198
	v_add_f32_e32 v145, v145, v199
	v_and_b32_e32 v149, 0xffff0000, v142
	v_add_f32_e32 v144, v144, v148
	v_add_f32_e32 v145, v145, v149
	v_lshlrev_b32_e32 v148, 16, v146
	v_and_b32_e32 v149, 0xffff0000, v146
	v_add_f32_e32 v144, v144, v148
	v_add_f32_e32 v145, v145, v149
	v_lshlrev_b32_e32 v148, 16, v150
	v_and_b32_e32 v149, 0xffff0000, v150
	v_add_f32_e32 v144, v144, v148
	v_add_f32_e32 v145, v145, v149
	v_and_b32_e32 v153, 0xffff0000, v154
	v_add_f32_e32 v144, v144, v152
	v_add_f32_e32 v145, v145, v153
	v_lshlrev_b32_e32 v152, 16, v158
	v_and_b32_e32 v153, 0xffff0000, v158
	v_add_f32_e32 v144, v144, v152
	v_add_f32_e32 v145, v145, v153
	v_lshlrev_b32_e32 v152, 16, v162
	v_and_b32_e32 v153, 0xffff0000, v162
	v_add_f32_e32 v144, v144, v152
	v_add_f32_e32 v145, v145, v153
	v_lshlrev_b32_e32 v146, 16, v147
	v_fma_f32 v144, v196, v144, -v148
	v_fma_f32 v145, v196, v145, -v149
	v_cvt_pk_bf16_f32 v142, v144, v145
	v_add_f32_e32 v144, 0, v170
	v_add_f32_e32 v145, 0, v171
	v_lshlrev_b32_e32 v148, 16, v143
	v_add_f32_e32 v144, v144, v200
	v_add_f32_e32 v145, v145, v201
	v_and_b32_e32 v149, 0xffff0000, v143
	v_add_f32_e32 v144, v144, v148
	v_add_f32_e32 v145, v145, v149
	v_and_b32_e32 v147, 0xffff0000, v147
	v_add_f32_e32 v144, v144, v146
	v_add_f32_e32 v145, v145, v147
	v_lshlrev_b32_e32 v146, 16, v151
	v_and_b32_e32 v147, 0xffff0000, v151
	v_add_f32_e32 v144, v144, v146
	v_add_f32_e32 v145, v145, v147
	v_lshlrev_b32_e32 v148, 16, v155
	v_and_b32_e32 v149, 0xffff0000, v155
	v_add_f32_e32 v144, v144, v148
	v_add_f32_e32 v145, v145, v149
	v_lshlrev_b32_e32 v148, 16, v159
	v_and_b32_e32 v149, 0xffff0000, v159
	v_add_f32_e32 v144, v144, v148
	v_add_f32_e32 v145, v145, v149
	v_lshlrev_b32_e32 v148, 16, v163
	v_and_b32_e32 v149, 0xffff0000, v163
	v_add_f32_e32 v144, v144, v148
	v_add_f32_e32 v145, v145, v149
	s_nop 0
	v_fma_f32 v144, v196, v144, -v146
	v_fma_f32 v145, v196, v145, -v147
	v_cvt_pk_bf16_f32 v143, v144, v145
	ds_read_b128 v[144:147], v244 offset:2176
	ds_read_b128 v[148:151], v244 offset:2704
	ds_read_b128 v[152:155], v244 offset:3232
	ds_read_b128 v[156:159], v244 offset:3760
	ds_read_b128 v[160:163], v244 offset:4288
	s_waitcnt lgkmcnt(4)
	v_lshlrev_b32_e32 v164, 16, v144
	v_and_b32_e32 v165, 0xffff0000, v144
	v_lshlrev_b32_e32 v144, 16, v145
	v_and_b32_e32 v145, 0xffff0000, v145
	v_add_f32_e32 v165, 0, v165
	s_waitcnt lgkmcnt(3)
	v_lshlrev_b32_e32 v166, 16, v148
	v_and_b32_e32 v167, 0xffff0000, v148
	v_lshlrev_b32_e32 v148, 16, v149
	v_and_b32_e32 v149, 0xffff0000, v149
	v_add_f32_e32 v164, v164, v166
	v_add_f32_e32 v165, v165, v167
	s_waitcnt lgkmcnt(2)
	v_lshlrev_b32_e32 v166, 16, v152
	v_and_b32_e32 v167, 0xffff0000, v152
	v_add_f32_e32 v144, v144, v148
	v_add_f32_e32 v145, v145, v149
	v_lshlrev_b32_e32 v148, 16, v153
	v_and_b32_e32 v149, 0xffff0000, v153
	v_lshlrev_b32_e32 v152, 16, v146
	v_and_b32_e32 v153, 0xffff0000, v146
	v_lshlrev_b32_e32 v146, 16, v147
	v_and_b32_e32 v147, 0xffff0000, v147
	v_add_f32_e32 v164, v164, v166
	v_add_f32_e32 v165, v165, v167
	s_waitcnt lgkmcnt(1)
	v_lshlrev_b32_e32 v166, 16, v156
	v_and_b32_e32 v167, 0xffff0000, v156
	v_add_f32_e32 v144, v144, v148
	v_add_f32_e32 v145, v145, v149
	v_lshlrev_b32_e32 v148, 16, v157
	v_and_b32_e32 v149, 0xffff0000, v157
	v_lshlrev_b32_e32 v156, 16, v150
	v_and_b32_e32 v157, 0xffff0000, v150
	v_lshlrev_b32_e32 v150, 16, v151
	v_and_b32_e32 v151, 0xffff0000, v151
	v_add_f32_e32 v152, v152, v156
	v_add_f32_e32 v153, v153, v157
	v_lshlrev_b32_e32 v156, 16, v154
	v_and_b32_e32 v157, 0xffff0000, v154
	v_add_f32_e32 v146, v146, v150
	v_add_f32_e32 v147, v147, v151
	v_lshlrev_b32_e32 v150, 16, v155
	v_and_b32_e32 v151, 0xffff0000, v155
	v_add_f32_e32 v152, v152, v156
	v_add_f32_e32 v153, v153, v157
	v_lshlrev_b32_e32 v156, 16, v158
	v_and_b32_e32 v157, 0xffff0000, v158
	v_add_f32_e32 v146, v146, v150
	v_add_f32_e32 v147, v147, v151
	v_lshlrev_b32_e32 v150, 16, v159
	v_and_b32_e32 v151, 0xffff0000, v159
	v_add_f32_e32 v164, v164, v166
	v_add_f32_e32 v165, v165, v167
	s_waitcnt lgkmcnt(0)
	v_lshlrev_b32_e32 v206, 16, v160
	v_and_b32_e32 v207, 0xffff0000, v160
	v_add_f32_e32 v148, v144, v148
	v_add_f32_e32 v149, v145, v149
	v_lshlrev_b32_e32 v144, 16, v161
	v_and_b32_e32 v145, 0xffff0000, v161
	v_add_f32_e32 v156, v152, v156
	v_add_f32_e32 v157, v153, v157
	v_lshlrev_b32_e32 v152, 16, v162
	v_and_b32_e32 v153, 0xffff0000, v162
	v_add_f32_e32 v150, v146, v150
	v_add_f32_e32 v151, v147, v151
	v_lshlrev_b32_e32 v146, 16, v163
	v_and_b32_e32 v147, 0xffff0000, v163
	v_add_f32_e32 v222, v164, v206
	v_add_f32_e32 v223, v165, v207
	v_add_f32_e32 v148, v148, v144
	v_add_f32_e32 v149, v149, v145
	v_add_f32_e32 v156, v156, v152
	v_add_f32_e32 v157, v157, v153
	v_add_f32_e32 v150, v150, v146
	v_add_f32_e32 v151, v151, v147
